# lever 7 in the stick-breaking tile block: the exposed first cross-half exchange pair by v_permlane32_swap + select on the VALU instead of two ds_bpermute round trips
# baseline (speedup 1.0000x reference)
.LBB0_465:
	s_cmp_ge_i32 s23, s4
	s_cselect_b64 s[16:17], -1, 0
	s_or_b64 s[16:17], s[16:17], s[14:15]
	s_and_b64 vcc, exec, s[16:17]
	s_cbranch_vccnz .LBB0_467
	s_add_i32 s98, s23, 94
	s_cmp_lt_i32 s98, s4
	s_cbranch_scc0 .Lsb_near
	v_add3_u32 v130, s18, v192, v205
	ds_read_b128 v[132:135], v130 offset:8704
	ds_read_b128 v[136:139], v130 offset:8736
	ds_read_b128 v[140:143], v130 offset:8768
	ds_read_b128 v[144:147], v130 offset:8800
	ds_read_b128 v[164:167], v130 offset:8832
	ds_read_b128 v[168:171], v130 offset:8864
	ds_read_b128 v[172:175], v130 offset:8896
	ds_read_b128 v[176:179], v130 offset:8928
	ds_read_b128 v[208:211], v130 offset:224
	v_add3_u32 v207, s22, v204, v206
	s_waitcnt lgkmcnt(8)
	v_mfma_f32_32x32x16_bf16 v[66:81], v[132:135], v[82:85], 0
	s_waitcnt lgkmcnt(7)
	v_mfma_f32_32x32x16_bf16 v[66:81], v[136:139], v[86:89], v[66:81]
	s_waitcnt lgkmcnt(6)
	v_mfma_f32_32x32x16_bf16 v[66:81], v[140:143], v[90:93], v[66:81]
	s_waitcnt lgkmcnt(5)
	v_mfma_f32_32x32x16_bf16 v[66:81], v[144:147], v[94:97], v[66:81]
	s_waitcnt lgkmcnt(4)
	v_mfma_f32_32x32x16_bf16 v[66:81], v[164:167], v[98:101], v[66:81]
	s_waitcnt lgkmcnt(3)
	v_mfma_f32_32x32x16_bf16 v[66:81], v[168:171], v[102:105], v[66:81]
	s_waitcnt lgkmcnt(2)
	v_mfma_f32_32x32x16_bf16 v[66:81], v[172:175], v[106:109], v[66:81]
	s_waitcnt lgkmcnt(1)
	v_mfma_f32_32x32x16_bf16 v[66:81], v[176:179], v[110:113], v[66:81]
	s_nop 11
	v_mov_b32_e32 v64, v66
	v_mov_b32_e32 v65, v68
	v_mov_b32_e32 v68, v67
	v_mul_f32_e32 v132, s68, v64
	v_mul_f32_e32 v133, s68, v65
	v_mov_b32_e32 v66, v70
	v_mul_f32_e32 v134, s68, v68
	v_mul_f32_e32 v135, s68, v69
	v_mul_f32_e64 v70, |v132|, s54
	v_mov_b32_e32 v67, v72
	v_mul_f32_e64 v72, |v134|, s54
	v_exp_f32_e32 v70, v70
	v_mul_f32_e64 v131, |v133|, s54
	v_exp_f32_e32 v72, v72
	v_mul_f32_e64 v138, |v135|, s54
	v_exp_f32_e32 v131, v131
	v_mul_f32_e32 v136, s68, v66
	v_mul_f32_e32 v137, s68, v67
	v_exp_f32_e32 v138, v138
	v_mul_f32_e64 v139, |v136|, s54
	v_add_f32_e32 v70, 1.0, v70
	v_exp_f32_e32 v139, v139
	v_add_f32_e32 v72, 1.0, v72
	v_add_f32_e32 v131, 1.0, v131
	v_add_f32_e32 v138, 1.0, v138
	v_log_f32_e32 v70, v70
	v_add_f32_e32 v139, 1.0, v139
	v_log_f32_e32 v72, v72
	v_log_f32_e32 v131, v131
	v_log_f32_e32 v138, v138
	v_mov_b32_e32 v142, v139
	v_mul_f32_e32 v139, 0x3f317217, v70
	v_mul_f32_e32 v140, 0x3f317217, v72
	v_fma_f32 v139, v70, s86, -v139
	v_mul_f32_e32 v141, 0x3f317217, v131
	v_fma_f32 v140, v72, s86, -v140
	v_fmac_f32_e32 v139, 0x3377d1cf, v70
	v_mul_f32_e32 v143, 0x3f317217, v138
	v_fma_f32 v141, v131, s86, -v141
	v_fmac_f32_e32 v140, 0x3377d1cf, v72
	v_fmac_f32_e32 v139, 0x3f317217, v70
	v_fma_f32 v143, v138, s86, -v143
	v_fmac_f32_e32 v141, 0x3377d1cf, v131
	v_fmac_f32_e32 v140, 0x3f317217, v72
	v_fmac_f32_e32 v143, 0x3377d1cf, v138
	v_fmac_f32_e32 v141, 0x3f317217, v131
	v_fmac_f32_e32 v143, 0x3f317217, v138
	v_min_f32_e32 v132, 0, v132
	v_min_f32_e32 v133, 0, v133
	v_sub_f32_e32 v166, v132, v139
	v_sub_f32_e32 v167, v133, v141
	v_fma_f32 v174, -v64, s68, v166
	v_fma_f32 v175, -v65, s68, v167
	v_log_f32_e32 v65, v142
	v_min_f32_e32 v134, 0, v134
	v_min_f32_e32 v135, 0, v135
	v_sub_f32_e32 v164, v134, v140
	v_sub_f32_e32 v165, v135, v143
	v_mov_b32_e32 v72, v71
	v_fma_f32 v172, -v68, s68, v164
	v_fma_f32 v173, -v69, s68, v165
	v_mul_f32_e32 v68, 0x3f317217, v65
	v_fma_f32 v70, v65, s86, -v68
	v_mul_f32_e32 v68, s68, v72
	v_mul_f32_e32 v69, s68, v73
	v_fmac_f32_e32 v70, 0x3377d1cf, v65
	v_mul_f32_e64 v71, |v68|, s54
	v_exp_f32_e32 v71, v71
	v_fmac_f32_e32 v70, 0x3f317217, v65
	v_mul_f32_e64 v131, |v137|, s54
	v_exp_f32_e32 v131, v131
	v_mov_b32_e32 v65, v70
	v_add_f32_e32 v70, 1.0, v71
	v_mul_f32_e64 v133, |v69|, s54
	v_exp_f32_e32 v133, v133
	v_log_f32_e32 v71, v70
	v_mov_b32_e32 v70, v65
	v_min_f32_e32 v64, 0, v136
	v_mul_f32_e32 v65, 0x3f317217, v71
	v_fma_f32 v65, v71, s86, -v65
	v_fmac_f32_e32 v65, 0x3377d1cf, v71
	v_fmac_f32_e32 v65, 0x3f317217, v71
	v_min_f32_e32 v68, 0, v68
	v_min_f32_e32 v69, 0, v69
	v_add_f32_e32 v71, 1.0, v131
	v_mov_b32_e32 v140, v78
	v_mov_b32_e32 v141, v80
	v_log_f32_e32 v71, v71
	v_mov_b32_e32 v132, v65
	v_min_f32_e32 v65, 0, v137
	v_mul_f32_e32 v131, 0x3f317217, v71
	v_fma_f32 v131, v71, s86, -v131
	v_fmac_f32_e32 v131, 0x3377d1cf, v71
	v_fmac_f32_e32 v131, 0x3f317217, v71
	v_mul_f32_e32 v142, s68, v140
	v_mul_f32_e32 v143, s68, v141
	v_mov_b32_e32 v80, v79
	v_mov_b32_e32 v71, v131
	v_add_f32_e32 v131, 1.0, v133
	v_sub_f32_e32 v168, v64, v70
	v_sub_f32_e32 v169, v65, v71
	v_log_f32_e32 v131, v131
	v_fma_f32 v176, -v66, s68, v168
	v_fma_f32 v177, -v67, s68, v169
	v_mul_f32_e32 v144, s68, v80
	v_mul_f32_e32 v145, s68, v81
	v_mul_f32_e32 v64, 0x3f317217, v131
	v_fma_f32 v70, v131, s86, -v64
	v_mov_b32_e32 v64, v74
	v_mul_f32_e32 v66, s68, v64
	v_mul_f32_e32 v67, s68, v76
	v_fmac_f32_e32 v70, 0x3377d1cf, v131
	v_mul_f32_e64 v71, |v66|, s54
	v_exp_f32_e32 v71, v71
	v_fmac_f32_e32 v70, 0x3f317217, v131
	v_min_f32_e32 v66, 0, v66
	v_mov_b32_e32 v133, v70
	v_add_f32_e32 v70, 1.0, v71
	v_sub_f32_e32 v170, v68, v132
	v_sub_f32_e32 v171, v69, v133
	ds_read_b128 v[132:135], v130 offset:32
	v_log_f32_e32 v70, v70
	v_fma_f32 v178, -v72, s68, v170
	v_fma_f32 v179, -v73, s68, v171
	v_mul_f32_e64 v73, |v67|, s54
	v_exp_f32_e32 v73, v73
	v_mul_f32_e32 v68, 0x3f317217, v70
	v_fma_f32 v71, v70, s86, -v68
	v_mul_f32_e32 v68, s68, v75
	v_mul_f32_e32 v69, s68, v77
	v_fmac_f32_e32 v71, 0x3377d1cf, v70
	v_mul_f32_e64 v72, |v68|, s54
	v_exp_f32_e32 v72, v72
	v_fmac_f32_e32 v71, 0x3f317217, v70
	v_mul_f32_e64 v74, |v69|, s54
	v_exp_f32_e32 v74, v74
	v_mov_b32_e32 v70, v71
	v_add_f32_e32 v71, 1.0, v72
	v_min_f32_e32 v67, 0, v67
	v_min_f32_e32 v68, 0, v68
	v_log_f32_e32 v71, v71
	v_min_f32_e32 v69, 0, v69
	v_mul_f32_e32 v72, 0x3f317217, v71
	v_fma_f32 v72, v71, s86, -v72
	v_fmac_f32_e32 v72, 0x3377d1cf, v71
	v_fmac_f32_e32 v72, 0x3f317217, v71
	s_nop 1
	v_mov_b32_e32 v71, v72
	v_add_f32_e32 v72, 1.0, v73
	s_nop 1
	v_log_f32_e32 v73, v72
	v_mov_b32_e32 v72, v71
	v_mul_f32_e32 v71, 0x3f317217, v73
	v_fma_f32 v71, v73, s86, -v71
	v_fmac_f32_e32 v71, 0x3377d1cf, v73
	v_fmac_f32_e32 v71, 0x3f317217, v73
	s_nop 1
	v_add_f32_e32 v73, 1.0, v74
	v_sub_f32_e32 v180, v66, v70
	v_sub_f32_e32 v181, v67, v71
	v_mul_f32_e64 v70, |v143|, s54
	v_log_f32_e32 v73, v73
	v_fma_f32 v184, -v64, s68, v180
	v_fma_f32 v185, -v76, s68, v181
	v_mul_f32_e64 v65, |v142|, s54
	v_exp_f32_e32 v65, v65
	v_mul_f32_e32 v64, 0x3f317217, v73
	v_fma_f32 v64, v73, s86, -v64
	v_fmac_f32_e32 v64, 0x3377d1cf, v73
	v_fmac_f32_e32 v64, 0x3f317217, v73
	v_exp_f32_e32 v131, v70
	v_mov_b32_e32 v73, v64
	v_add_f32_e32 v64, 1.0, v65
	v_mul_f32_e64 v66, |v144|, s54
	v_exp_f32_e32 v66, v66
	v_log_f32_e32 v64, v64
	v_sub_f32_e32 v182, v68, v72
	v_sub_f32_e32 v183, v69, v73
	v_add_f32_e32 v131, 1.0, v131
	v_fma_f32 v186, -v75, s68, v182
	v_fma_f32 v187, -v77, s68, v183
	v_mul_f32_e32 v65, 0x3f317217, v64
	v_fma_f32 v65, v64, s86, -v65
	v_fmac_f32_e32 v65, 0x3377d1cf, v64
	v_fmac_f32_e32 v65, 0x3f317217, v64
	v_min_f32_e32 v142, 0, v142
	v_min_f32_e32 v143, 0, v143
	v_mov_b32_e32 v64, v65
	v_add_f32_e32 v65, 1.0, v66
	v_min_f32_e32 v144, 0, v144
	v_log_f32_e32 v68, v65
	v_mov_b32_e32 v146, v64
	ds_read_b128 v[64:67], v130
	v_mul_f32_e32 v69, 0x3f317217, v68
	v_fma_f32 v69, v68, s86, -v69
	v_fmac_f32_e32 v69, 0x3377d1cf, v68
	v_fmac_f32_e32 v69, 0x3f317217, v68
	s_nop 0
	v_mov_b32_e32 v147, v69
	s_waitcnt lgkmcnt(0)
	v_mfma_f32_32x32x16_bf16 v[64:79], v[64:67], v[82:85], 0
	v_mov_b32_e32 v148, v147
	s_nop 0
	ds_read_b128 v[136:139], v130 offset:64
	v_log_f32_e32 v131, v131
	v_mfma_f32_32x32x16_bf16 v[64:79], v[132:135], v[86:89], v[64:79]
	v_mul_f32_e32 v132, 0x3f317217, v131
	v_fma_f32 v147, v131, s86, -v132
	ds_read_b128 v[132:135], v130 offset:96
	v_fmac_f32_e32 v147, 0x3377d1cf, v131
	v_fmac_f32_e32 v147, 0x3f317217, v131
	s_waitcnt lgkmcnt(1)
	v_mfma_f32_32x32x16_bf16 v[64:79], v[136:139], v[90:93], v[64:79]
	v_mul_f32_e64 v137, |v145|, s54
	v_exp_f32_e32 v149, v137
	ds_read_b128 v[136:139], v130 offset:128
	s_waitcnt lgkmcnt(1)
	v_mfma_f32_32x32x16_bf16 v[64:79], v[132:135], v[94:97], v[64:79]
	v_add_f32_e32 v131, 1.0, v149
	v_add_f32_e64 v188, v142, -v146
	v_add_f32_e64 v189, v143, -v147
	v_min_f32_e32 v145, 0, v145
	ds_read_b128 v[132:135], v130 offset:160
	s_waitcnt lgkmcnt(1)
	v_mfma_f32_32x32x16_bf16 v[64:79], v[136:139], v[98:101], v[64:79]
	v_log_f32_e32 v131, v131
	v_fma_f32 v212, -v140, s68, v188
	v_fma_f32 v213, -v141, s68, v189
	v_mul_f32_e32 v136, 0x3f317217, v131
	v_fma_f32 v140, v131, s86, -v136
	ds_read_b128 v[136:139], v130 offset:192
	s_waitcnt lgkmcnt(1)
	v_mfma_f32_32x32x16_bf16 v[64:79], v[132:135], v[102:105], v[64:79]
	v_fmac_f32_e32 v140, 0x3377d1cf, v131
	v_fmac_f32_e32 v140, 0x3f317217, v131
	s_nop 0
	s_waitcnt lgkmcnt(0)
	v_mfma_f32_32x32x16_bf16 v[64:79], v[136:139], v[106:109], v[64:79]
	v_add_f32_e64 v190, v144, -v148
	v_add_f32_e64 v191, v145, -v140
	ds_read_b64_tr_b16 v[146:147], v207 offset:45056
	ds_read_b64_tr_b16 v[142:143], v207 offset:45120
	ds_read_b64_tr_b16 v[138:139], v207 offset:45184
	ds_read_b64_tr_b16 v[134:135], v207 offset:45248
	ds_read_b64_tr_b16 v[148:149], v207 offset:47616
	ds_read_b64_tr_b16 v[144:145], v207 offset:47680
	ds_read_b64_tr_b16 v[140:141], v207 offset:47744
	ds_read_b64_tr_b16 v[136:137], v207 offset:47808
	ds_read_b64_tr_b16 v[130:131], v207 offset:50176
	ds_read_b64_tr_b16 v[132:133], v207 offset:52736
	v_fma_f32 v216, -v80, s68, v190
	v_fma_f32 v217, -v81, s68, v191
	v_mfma_f32_32x32x16_bf16 v[64:79], v[208:211], v[110:113], v[64:79]
	v_mov_b32_e32 v80, v174
	v_mov_b32_e32 v81, v175
	v_mov_b32_e32 v174, v172
	v_mov_b32_e32 v175, v173
	v_add_f32_e32 v80, v80, v174
	v_add_f32_e32 v81, v81, v175
	v_add_f32_e32 v172, v80, v81
	v_add_f32_e32 v173, v81, v80
	v_mov_b32_e32 v210, v216
	v_add_f32_e32 v184, v184, v186
	v_add_f32_e32 v185, v185, v187
	v_add_f32_e32 v208, v212, v210
	v_add_f32_e32 v209, v213, v217
	v_add_f32_e32 v240, v184, v185
	v_add_f32_e32 v241, v185, v184
	v_add_f32_e32 v212, v208, v209
	v_add_f32_e32 v213, v209, v208
	s_waitcnt lgkmcnt(0)
	v_mov_b32_e32 v216, v212
	v_mov_b32_e32 v184, v240
	v_mov_b32_e32 v248, v212
	v_mov_b32_e32 v249, v240
	s_nop 0
	v_permlane32_swap_b32_e32 v248, v216
	v_permlane32_swap_b32_e32 v249, v184
	v_cndmask_b32_e64 v216, v248, v216, s[10:11]
	v_cndmask_b32_e64 v184, v249, v184, s[10:11]
	v_add_f32_e32 v208, v212, v216
	v_cndmask_b32_e64 v213, 0, v184, s[10:11]
	v_add_f32_e32 v208, v213, v208
	v_add_f32_e32 v245, v162, v208
	v_add_f32_e32 v246, v186, v185
	v_add_f32_e32 v247, v180, v245
	v_add_f32_e32 v182, v182, v245
	v_add_f32_e32 v180, v246, v247
	v_mul_f32_e32 v180, 0x3fb8aa3b, v180
	v_exp_f32_e32 v180, v180
	v_add_f32_e32 v182, v185, v182
	v_mul_f32_e32 v182, 0x3fb8aa3b, v182
	v_exp_f32_e32 v182, v182
	v_add_f32_e32 v176, v176, v178
	v_add_f32_e32 v177, v177, v179
	v_mov_b32_e32 v213, v180
	v_add_f32_e32 v180, v181, v245
	v_add_f32_e32 v242, v176, v177
	v_add_f32_e32 v243, v177, v176
	v_add_f32_e32 v180, v187, v180
	ds_bpermute_b32 v80, v235, v172
	ds_bpermute_b32 v176, v235, v242
	v_mul_f32_e32 v180, 0x3fb8aa3b, v180
	v_mov_b32_e32 v215, v182
	v_exp_f32_e32 v239, v180
	v_add_f32_e32 v180, v183, v245
	v_add_f32_e32 v182, v184, v216
	v_add_f32_e32 v183, v240, v212
	v_add_f32_e32 v180, 0, v180
	v_add_f32_e32 v181, v242, v183
	v_add_f32_e32 v181, v181, v216
	v_add_f32_e32 v181, v181, v184
	v_cndmask_b32_e64 v173, 0, v216, s[10:11]
	s_waitcnt lgkmcnt(1)
	v_cndmask_b32_e64 v208, 0, v80, s[10:11]
	v_mul_f32_e32 v180, 0x3fb8aa3b, v180
	s_waitcnt lgkmcnt(0)
	v_add_f32_e32 v181, v181, v176
	v_exp_f32_e32 v241, v180
	v_add_f32_e32 v180, v162, v173
	v_add_f32_e32 v173, v183, v216
	v_add_f32_e32 v181, v208, v181
	v_cndmask_b32_e64 v186, 0, v176, s[10:11]
	v_add_f32_e32 v173, v173, v184
	v_add_f32_e32 v185, v162, v181
	v_add_f32_e32 v173, v186, v173
	v_add_f32_e32 v164, v164, v185
	v_add_f32_e32 v186, v174, v81
	v_add_f32_e32 v187, v166, v185
	v_add_f32_e32 v81, v81, v164
	v_add_f32_e32 v164, v167, v185
	v_add_f32_e32 v165, v165, v185
	v_add_f32_e32 v166, v186, v187
	v_add_f32_e32 v164, v175, v164
	v_add_f32_e32 v165, 0, v165
	v_mul_f32_e32 v166, 0x3fb8aa3b, v166
	v_mul_f32_e32 v164, 0x3fb8aa3b, v164
	v_mul_f32_e32 v165, 0x3fb8aa3b, v165
	v_exp_f32_e32 v166, v166
	v_exp_f32_e32 v164, v164
	v_exp_f32_e32 v165, v165
	v_mov_b32_e32 v174, v166
	v_mov_b32_e32 v175, v164
	v_mov_b32_e32 v181, v165
	v_add_f32_e32 v165, v162, v173
	v_add_f32_e32 v166, v178, v177
	v_add_f32_e32 v167, v168, v165
	v_mul_f32_e32 v81, 0x3fb8aa3b, v81
	v_add_f32_e32 v164, v166, v167
	v_add_f32_e32 v166, v170, v165
	v_add_f32_e32 v167, v169, v165
	v_add_f32_e32 v165, v171, v165
	v_add_f32_e32 v166, v177, v166
	v_add_f32_e32 v167, v179, v167
	v_add_f32_e32 v165, 0, v165
	v_mul_f32_e32 v164, 0x3fb8aa3b, v164
	v_mul_f32_e32 v166, 0x3fb8aa3b, v166
	v_mul_f32_e32 v167, 0x3fb8aa3b, v167
	v_mul_f32_e32 v165, 0x3fb8aa3b, v165
	v_exp_f32_e32 v81, v81
	v_exp_f32_e32 v164, v164
	v_exp_f32_e32 v166, v166
	v_exp_f32_e32 v167, v167
	v_exp_f32_e32 v165, v165
	v_mov_b32_e32 v168, v164
	v_mov_b32_e32 v169, v165
	v_cvt_pk_bf16_f32 v164, v174, v81
	v_cvt_pk_bf16_f32 v165, v175, v181
	v_cvt_pk_bf16_f32 v166, v168, v166
	v_cvt_pk_bf16_f32 v167, v167, v169
	s_nop 0
	s_nop 0
	v_mfma_f32_32x32x16_bf16 v[48:63], v[146:149], v[164:167], v[48:63]
	v_add_f32_e64 v146, v180, v188
	v_add_f32_e64 v147, v210, v209
	v_add_f32_e32 v81, v146, v147
	v_mul_f32_e32 v81, 0x3fb8aa3b, v81
	v_exp_f32_e32 v81, v81
	v_mfma_f32_32x32x16_bf16 v[32:47], v[142:145], v[164:167], v[32:47]
	v_add_f32_e32 v143, v180, v190
	v_add_f32_e32 v144, v180, v189
	v_add_f32_e32 v143, v143, v209
	v_mul_f32_e32 v143, 0x3fb8aa3b, v143
	v_exp_f32_e32 v143, v143
	v_mfma_f32_32x32x16_bf16 v[16:31], v[138:141], v[164:167], v[16:31]
	v_add_f32_e32 v139, v180, v191
	v_add_f32_e32 v138, v144, v217
	v_add_f32_e32 v139, 0, v139
	v_mul_f32_e32 v138, 0x3fb8aa3b, v138
	v_mul_f32_e32 v139, 0x3fb8aa3b, v139
	v_exp_f32_e32 v138, v138
	v_exp_f32_e32 v139, v139
	v_mfma_f32_32x32x16_bf16 v[0:15], v[134:137], v[164:167], v[0:15]
	v_cvt_pk_bf16_f32 v134, v213, v215
	v_cvt_pk_bf16_f32 v135, v239, v241
	v_cvt_pk_bf16_f32 v136, v81, v143
	v_cvt_pk_bf16_f32 v137, v138, v139
	ds_read_b64_tr_b16 v[138:139], v207 offset:50240
	ds_read_b64_tr_b16 v[142:143], v207 offset:50304
	ds_read_b64_tr_b16 v[146:147], v207 offset:50368
	ds_read_b64_tr_b16 v[140:141], v207 offset:52800
	ds_read_b64_tr_b16 v[144:145], v207 offset:52864
	ds_read_b64_tr_b16 v[148:149], v207 offset:52928
	v_mfma_f32_32x32x16_bf16 v[48:63], v[130:133], v[134:137], v[48:63]
	v_mov_b32_e32 v130, v64
	v_mov_b32_e32 v131, v68
	v_mul_f32_e64 v132, v130, s68
	v_mul_f32_e64 v133, v131, s68
	v_mul_f32_e64 v64, |v132|, s54
	v_exp_f32_e32 v64, v64
	v_add_f32_e32 v80, v80, v176
	v_add_f32_e32 v81, v172, v242
	s_waitcnt lgkmcnt(2)
	v_mfma_f32_32x32x16_bf16 v[32:47], v[138:141], v[134:137], v[32:47]
	v_add_f32_e64 v80, v80, v182
	v_add_f32_e64 v81, v81, v183
	v_add_f32_e32 v64, 1.0, v64
	s_nop 1
	v_log_f32_e32 v138, v64
	v_min_f32_e32 v64, 0, v132
	s_waitcnt lgkmcnt(1)
	v_mfma_f32_32x32x16_bf16 v[16:31], v[142:145], v[134:137], v[16:31]
	v_mul_f32_e64 v143, |v133|, s54
	v_mul_f32_e32 v68, 0x3f317217, v138
	v_fma_f32 v132, v138, s86, -v68
	v_mov_b32_e32 v68, v65
	v_fmac_f32_e32 v132, 0x3377d1cf, v138
	v_fmac_f32_e32 v132, 0x3f317217, v138
	s_waitcnt lgkmcnt(0)
	v_mfma_f32_32x32x16_bf16 v[0:15], v[146:149], v[134:137], v[0:15]
	v_mul_f32_e64 v134, v68, s68
	v_mul_f32_e64 v135, v69, s68
	v_mul_f32_e64 v65, |v134|, s54
	v_exp_f32_e32 v65, v65
	v_mov_b32_e32 v137, v70
	v_exp_f32_e32 v143, v143
	v_min_f32_e32 v134, 0, v134
	v_add_f32_e32 v65, 1.0, v65
	v_add_f32_e32 v143, 1.0, v143
	s_nop 0
	v_log_f32_e32 v65, v65
	s_nop 0
	v_mul_f32_e32 v136, 0x3f317217, v65
	v_fma_f32 v140, v65, s86, -v136
	v_mov_b32_e32 v136, v66
	v_mul_f32_e32 v138, s68, v136
	v_mul_f32_e32 v139, s68, v137
	v_fmac_f32_e32 v140, 0x3377d1cf, v65
	v_mul_f32_e64 v66, |v138|, s54
	v_exp_f32_e32 v66, v66
	v_fmac_f32_e32 v140, 0x3f317217, v65
	v_min_f32_e32 v138, 0, v138
	v_add_f32_e32 v66, 1.0, v66
	v_mov_b32_e32 v65, v140
	s_nop 1
	v_log_f32_e32 v142, v66
	v_mov_b32_e32 v70, v67
	v_mul_f32_e32 v140, s68, v70
	v_mul_f32_e32 v141, s68, v71
	v_mul_f32_e64 v67, |v140|, s54
	v_exp_f32_e32 v67, v67
	v_mov_b32_e32 v66, v65
	v_mul_f32_e32 v65, 0x3f317217, v142
	v_fma_f32 v65, v142, s86, -v65
	v_fmac_f32_e32 v65, 0x3377d1cf, v142
	v_fmac_f32_e32 v65, 0x3f317217, v142
	v_add_f32_e32 v67, 1.0, v67
	v_min_f32_e32 v140, 0, v140
	s_nop 1
	v_log_f32_e32 v67, v67
	v_mov_b32_e32 v142, v65
	v_mul_f32_e32 v65, 0x3f317217, v67
	v_fma_f32 v65, v67, s86, -v65
	v_fmac_f32_e32 v65, 0x3377d1cf, v67
	v_fmac_f32_e32 v65, 0x3f317217, v67
	s_nop 1
	s_nop 0
	v_log_f32_e32 v143, v143
	v_mov_b32_e32 v144, v65
	v_min_f32_e32 v65, 0, v133
	v_mul_f32_e32 v133, 0x3f317217, v143
	v_fma_f32 v133, v143, s86, -v133
	v_fmac_f32_e32 v133, 0x3377d1cf, v143
	v_fmac_f32_e32 v133, 0x3f317217, v143
	s_nop 1
	v_sub_f32_e32 v64, v64, v132
	v_sub_f32_e32 v65, v65, v133
	v_mul_f32_e64 v132, |v135|, s54
	v_exp_f32_e32 v132, v132
	v_fma_f32 v130, -v130, s68, v64
	v_fma_f32 v131, -v131, s68, v65
	v_add_f32_e32 v67, 1.0, v132
	v_mov_b32_e32 v146, v130
	v_min_f32_e32 v135, 0, v135
	v_log_f32_e32 v67, v67
	v_mov_b32_e32 v147, v131
	v_mul_f32_e32 v132, 0x3f317217, v67
	v_fma_f32 v132, v67, s86, -v132
	v_fmac_f32_e32 v132, 0x3377d1cf, v67
	v_fmac_f32_e32 v132, 0x3f317217, v67
	s_nop 1
	v_mov_b32_e32 v67, v132
	v_mul_f32_e64 v132, |v139|, s54
	v_sub_f32_e32 v66, v134, v66
	v_sub_f32_e32 v67, v135, v67
	v_exp_f32_e32 v134, v132
	v_fma_f32 v68, -v68, s68, v66
	v_fma_f32 v69, -v69, s68, v67
	v_min_f32_e32 v139, 0, v139
	v_mov_b32_e32 v132, v68
	v_add_f32_e32 v68, 1.0, v134
	v_mov_b32_e32 v133, v69
	v_log_f32_e32 v68, v68
	s_nop 0
	v_mul_f32_e32 v69, 0x3f317217, v68
	v_fma_f32 v69, v68, s86, -v69
	v_fmac_f32_e32 v69, 0x3377d1cf, v68
	v_fmac_f32_e32 v69, 0x3f317217, v68
	s_nop 1
	v_sub_f32_e32 v68, v138, v142
	v_sub_f32_e32 v69, v139, v69
	v_fma_f32 v130, -v136, s68, v68
	v_fma_f32 v131, -v137, s68, v69
	v_mul_f32_e64 v136, |v141|, s54
	v_exp_f32_e32 v136, v136
	v_mov_b32_e32 v142, v130
	v_mov_b32_e32 v143, v131
	v_mul_f32_e32 v134, s68, v72
	v_mul_f32_e32 v135, s68, v73
	v_add_f32_e32 v130, 1.0, v136
	v_mul_f32_e64 v138, |v134|, s54
	v_exp_f32_e32 v138, v138
	v_log_f32_e32 v130, v130
	s_nop 0
	v_mul_f32_e32 v131, 0x3f317217, v130
	v_fma_f32 v131, v130, s86, -v131
	v_fmac_f32_e32 v131, 0x3377d1cf, v130
	v_fmac_f32_e32 v131, 0x3f317217, v130
	v_min_f32_e32 v134, 0, v134
	v_min_f32_e32 v141, 0, v141
	v_add_f32_e32 v136, 1.0, v138
	v_sub_f32_e32 v130, v140, v144
	v_sub_f32_e32 v131, v141, v131
	v_log_f32_e32 v136, v136
	v_mul_f32_e64 v138, |v135|, s54
	v_exp_f32_e32 v138, v138
	v_min_f32_e32 v135, 0, v135
	v_mul_f32_e32 v137, 0x3f317217, v136
	v_fma_f32 v137, v136, s86, -v137
	v_fmac_f32_e32 v137, 0x3377d1cf, v136
	v_fmac_f32_e32 v137, 0x3f317217, v136
	v_mov_b32_e32 v136, v137
	v_add_f32_e32 v137, 1.0, v138
	v_fma_f32 v70, -v70, s68, v130
	v_fma_f32 v71, -v71, s68, v131
	s_nop 0
	v_log_f32_e32 v137, v137
	s_nop 0
	v_mul_f32_e32 v138, 0x3f317217, v137
	v_fma_f32 v138, v137, s86, -v138
	v_fmac_f32_e32 v138, 0x3377d1cf, v137
	v_fmac_f32_e32 v138, 0x3f317217, v137
	s_nop 0
	v_sub_f32_e32 v134, v134, v136
	v_sub_f32_e32 v135, v135, v138
	v_mul_f32_e32 v136, s68, v74
	v_mul_f32_e32 v137, s68, v75
	v_mul_f32_e64 v139, |v136|, s54
	v_exp_f32_e32 v139, v139
	v_mul_f32_e64 v140, |v137|, s54
	v_exp_f32_e32 v140, v140
	v_add_f32_e32 v138, 1.0, v139
	v_min_f32_e32 v136, 0, v136
	v_min_f32_e32 v137, 0, v137
	v_log_f32_e32 v138, v138
	v_fma_f32 v72, -v72, s68, v134
	v_fma_f32 v73, -v73, s68, v135
	v_mul_f32_e32 v139, 0x3f317217, v138
	v_fma_f32 v139, v138, s86, -v139
	v_fmac_f32_e32 v139, 0x3377d1cf, v138
	v_fmac_f32_e32 v139, 0x3f317217, v138
	v_mov_b32_e32 v138, v139
	v_add_f32_e32 v139, 1.0, v140
	s_nop 1
	v_log_f32_e32 v139, v139
	s_nop 0
	v_mul_f32_e32 v140, 0x3f317217, v139
	v_fma_f32 v140, v139, s86, -v140
	v_fmac_f32_e32 v140, 0x3377d1cf, v139
	v_fmac_f32_e32 v140, 0x3f317217, v139
	s_nop 1
	v_mov_b32_e32 v139, v140
	v_add_f32_e32 v140, v142, v70
	v_add_f32_e32 v141, v143, v71
	v_mov_b32_e32 v142, v76
	v_mov_b32_e32 v143, v78
	v_mul_f32_e32 v144, s68, v142
	v_mul_f32_e32 v145, s68, v143
	v_sub_f32_e32 v136, v136, v138
	v_sub_f32_e32 v137, v137, v139
	v_mul_f32_e64 v76, |v144|, s54
	v_exp_f32_e32 v78, v76
	v_fma_f32 v74, -v74, s68, v136
	v_fma_f32 v75, -v75, s68, v137
	v_mov_b32_e32 v138, v74
	v_mul_f32_e64 v149, |v145|, s54
	v_mov_b32_e32 v139, v75
	v_add_f32_e32 v74, v146, v132
	v_add_f32_e32 v75, v147, v133
	v_exp_f32_e32 v149, v149
	v_add_f32_e32 v146, v74, v140
	v_add_f32_e32 v147, v75, v141
	v_add_f32_e32 v74, 1.0, v78
	ds_bpermute_b32 v148, v235, v147
	ds_bpermute_b32 v76, v235, v146
	v_log_f32_e32 v75, v74
	s_nop 0
	v_mul_f32_e32 v78, 0x3f317217, v75
	v_add_f32_e32 v164, v72, v73
	v_add_f32_e32 v165, v73, v75
	v_min_f32_e32 v74, 0, v144
	v_fma_f32 v144, v75, s86, -v78
	v_mov_b32_e32 v78, v77
	v_mul_f32_e32 v166, s68, v78
	v_mul_f32_e32 v167, s68, v79
	v_fmac_f32_e32 v144, 0x3377d1cf, v75
	v_mul_f32_e64 v77, |v166|, s54
	v_exp_f32_e32 v77, v77
	v_fmac_f32_e32 v144, 0x3f317217, v75
	v_min_f32_e32 v166, 0, v166
	v_add_f32_e32 v77, 1.0, v77
	v_log_f32_e32 v77, v77
	s_nop 0
	v_mul_f32_e32 v75, 0x3f317217, v77
	v_fma_f32 v75, v77, s86, -v75
	v_fmac_f32_e32 v75, 0x3377d1cf, v77
	v_fmac_f32_e32 v75, 0x3f317217, v77
	s_nop 1
	v_mov_b32_e32 v168, v75
	v_add_f32_e32 v75, 1.0, v149
	s_nop 0
	v_log_f32_e32 v77, v75
	v_min_f32_e32 v75, 0, v145
	v_mul_f32_e32 v145, 0x3f317217, v77
	v_fma_f32 v145, v77, s86, -v145
	v_fmac_f32_e32 v145, 0x3377d1cf, v77
	v_fmac_f32_e32 v145, 0x3f317217, v77
	s_nop 1
	v_mul_f32_e64 v77, |v167|, s54
	v_exp_f32_e32 v77, v77
	v_sub_f32_e32 v74, v74, v144
	v_sub_f32_e32 v75, v75, v145
	v_min_f32_e32 v167, 0, v167
	v_add_f32_e32 v77, 1.0, v77
	v_log_f32_e32 v77, v77
	v_fma_f32 v142, -v142, s68, v74
	v_fma_f32 v143, -v143, s68, v75
	v_mul_f32_e32 v144, 0x3f317217, v77
	v_fma_f32 v144, v77, s86, -v144
	v_fmac_f32_e32 v144, 0x3377d1cf, v77
	v_fmac_f32_e32 v144, 0x3f317217, v77
	v_mov_b32_e32 v169, v144
	v_sub_f32_e32 v144, v166, v168
	v_sub_f32_e32 v145, v167, v169
	v_fma_f32 v78, -v78, s68, v144
	v_fma_f32 v79, -v79, s68, v145
	v_mov_b32_e32 v167, v79
	v_mov_b32_e32 v168, v132
	v_mov_b32_e32 v166, v78
	v_add_f32_e32 v142, v142, v166
	v_add_f32_e32 v143, v143, v167
	v_add_f32_e32 v170, v138, v139
	v_add_f32_e32 v171, v139, v133
	v_add_f32_e32 v164, v164, v170
	v_add_f32_e32 v165, v142, v143
	ds_bpermute_b32 v149, v235, v165
	ds_bpermute_b32 v77, v235, v164
	v_add_f32_e32 v78, v146, v146
	v_add_f32_e32 v79, v146, v147
	v_mov_b32_e32 v169, v64
	v_mov_b32_e32 v64, v133
	v_add_f32_e32 v132, v164, v165
	v_add_f32_e32 v133, v165, v164
	s_waitcnt lgkmcnt(1)
	v_add_f32_e32 v142, v165, v149
	s_waitcnt lgkmcnt(0)
	v_cndmask_b32_e64 v146, 0, v77, s[10:11]
	v_add_f32_e32 v142, v146, v142
	v_add_f32_e32 v146, v132, v149
	v_add_f32_e32 v147, v147, v132
	v_add_f32_e32 v146, v146, v77
	v_cndmask_b32_e64 v163, 0, v148, s[10:11]
	v_add_f32_e32 v147, v147, v149
	v_add_f32_e32 v146, v163, v146
	v_add_f32_e32 v147, v147, v77
	v_cndmask_b32_e64 v163, 0, v76, s[10:11]
	v_add_f32_e32 v76, v76, v148
	v_add_f32_e32 v77, v77, v149
	v_mov_b32_e32 v78, v80
	v_add_f32_e32 v147, v147, v148
	v_add_f32_e32 v77, v76, v77
	v_add_f32_e32 v76, v76, v76
	v_pk_mov_b32 v[80:81], v[80:81], v[132:133] op_sel:[1,0]
	v_add_f32_e32 v147, v163, v147
	v_add_f32_e32 v78, v78, v80
	v_add_f32_e32 v79, v79, v81
	v_mov_b32_e32 v163, v77
	v_add_f32_e32 v80, v162, v78
	v_add_f32_e32 v81, v163, v79
	v_add_f32_e32 v77, v80, v147
	v_add_f32_e32 v78, v168, v140
	v_add_f32_e32 v79, v169, v77
	v_add_f32_e32 v68, v68, v77
	v_add_f32_e32 v76, v78, v79
	v_mul_f32_e32 v76, 0x3fb8aa3b, v76
	v_exp_f32_e32 v76, v76
	v_add_f32_e32 v66, v66, v77
	v_add_f32_e32 v68, v70, v68
	v_add_f32_e32 v70, v130, v77
	v_mov_b32_e32 v78, v76
	v_add_f32_e32 v77, v80, v146
	v_add_f32_e32 v66, v140, v66
	v_add_f32_e32 v64, v64, v141
	v_add_f32_e32 v65, v65, v77
	v_mul_f32_e32 v66, 0x3fb8aa3b, v66
	v_add_f32_e32 v64, v64, v65
	v_add_f32_e32 v65, v67, v77
	v_exp_f32_e32 v66, v66
	v_add_f32_e32 v65, v141, v65
	v_mul_f32_e32 v64, 0x3fb8aa3b, v64
	v_mul_f32_e32 v65, 0x3fb8aa3b, v65
	v_exp_f32_e32 v64, v64
	v_exp_f32_e32 v65, v65
	v_mov_b32_e32 v79, v66
	v_add_f32_e32 v66, v69, v77
	v_add_f32_e32 v66, v71, v66
	v_mul_f32_e32 v66, 0x3fb8aa3b, v66
	v_mov_b32_e32 v71, v64
	v_mov_b32_e32 v76, v65
	v_add_f32_e32 v171, v80, v142
	v_pk_mov_b32 v[64:65], v[72:73], v[134:135] op_sel:[1,0]
	v_exp_f32_e32 v66, v66
	v_add_f32_e32 v67, v131, v77
	v_add_f32_e32 v64, v64, v170
	v_add_f32_e32 v65, v65, v171
	v_add_f32_e32 v67, 0, v67
	v_add_f32_e32 v64, v64, v65
	v_add_f32_e32 v65, v135, v171
	v_mul_f32_e32 v67, 0x3fb8aa3b, v67
	v_mul_f32_e32 v64, 0x3fb8aa3b, v64
	v_add_f32_e32 v65, v170, v65
	v_exp_f32_e32 v67, v67
	v_exp_f32_e32 v64, v64
	v_mul_f32_e32 v65, 0x3fb8aa3b, v65
	v_add_f32_e32 v70, 0, v70
	v_mov_b32_e32 v77, v66
	v_exp_f32_e32 v140, v65
	v_add_f32_e32 v65, v136, v171
	v_add_f32_e32 v66, v137, v171
	v_mul_f32_e32 v68, 0x3fb8aa3b, v68
	v_mul_f32_e32 v70, 0x3fb8aa3b, v70
	v_add_f32_e32 v65, v139, v65
	v_add_f32_e32 v66, 0, v66
	v_exp_f32_e32 v68, v68
	v_exp_f32_e32 v70, v70
	v_mul_f32_e32 v65, 0x3fb8aa3b, v65
	v_mul_f32_e32 v66, 0x3fb8aa3b, v66
	v_mov_b32_e32 v131, v67
	v_exp_f32_e32 v139, v66
	v_exp_f32_e32 v141, v65
	v_mov_b32_e32 v146, v64
	ds_read_b64_tr_b16 v[64:65], v207 offset:34816
	ds_read_b64_tr_b16 v[66:67], v207 offset:37376
	v_cndmask_b32_e64 v138, 0, v149, s[10:11]
	v_add_f32_e32 v72, v80, v138
	v_mov_b32_e32 v142, v74
	v_mov_b32_e32 v130, v68
	v_add_f32_e32 v68, v72, v142
	v_add_f32_e32 v69, v166, v143
	v_mov_b32_e32 v74, v139
	v_add_f32_e32 v73, v68, v69
	v_cvt_pk_bf16_f32 v68, v78, v79
	v_cvt_pk_bf16_f32 v69, v130, v70
	v_cvt_pk_bf16_f32 v70, v71, v76
	v_cvt_pk_bf16_f32 v71, v77, v131
	ds_read_b64_tr_b16 v[76:77], v207 offset:34880
	ds_read_b64_tr_b16 v[130:131], v207 offset:34944
	ds_read_b64_tr_b16 v[134:135], v207 offset:35008
	ds_read_b64_tr_b16 v[78:79], v207 offset:37440
	ds_read_b64_tr_b16 v[132:133], v207 offset:37504
	ds_read_b64_tr_b16 v[136:137], v207 offset:37568
	s_waitcnt lgkmcnt(6)
	v_mfma_f32_32x32x16_bf16 v[48:63], v[64:67], v[68:71], v[48:63]
	v_mul_f32_e32 v64, 0x3fb8aa3b, v73
	v_exp_f32_e32 v64, v64
	v_add_f32_e32 v65, v72, v75
	v_add_f32_e32 v65, v65, v167
	v_mul_f32_e32 v65, 0x3fb8aa3b, v65
	v_mov_b32_e32 v139, v64
	v_add_f32_e32 v64, v72, v144
	v_exp_f32_e32 v75, v65
	v_add_f32_e32 v65, v72, v145
	v_add_f32_e32 v64, v64, v143
	v_add_f32_e32 v65, 0, v65
	v_mul_f32_e32 v64, 0x3fb8aa3b, v64
	v_mul_f32_e32 v65, 0x3fb8aa3b, v65
	v_exp_f32_e32 v64, v64
	v_exp_f32_e32 v72, v65
	s_waitcnt lgkmcnt(2)
	v_mfma_f32_32x32x16_bf16 v[32:47], v[76:79], v[68:71], v[32:47]
	v_mov_b32_e32 v138, v141
	v_mov_b32_e32 v76, v64
	ds_read_b64_tr_b16 v[64:65], v207 offset:39936
	ds_read_b64_tr_b16 v[66:67], v207 offset:42496
	v_add_f32_e32 v162, v80, v81
	s_mov_b32 s14, 0xc2480000
	s_waitcnt lgkmcnt(3)
	v_mfma_f32_32x32x16_bf16 v[16:31], v[130:133], v[68:71], v[16:31]
	v_cmp_gt_f32_e32 vcc, s14, v162
	s_cmp_eq_u64 vcc, exec
	s_cselect_b64 s[14:15], -1, 0
	s_waitcnt lgkmcnt(2)
	v_mfma_f32_32x32x16_bf16 v[0:15], v[134:137], v[68:71], v[0:15]
	v_cvt_pk_bf16_f32 v68, v146, v140
	v_cvt_pk_bf16_f32 v69, v138, v74
	v_cvt_pk_bf16_f32 v70, v139, v76
	v_cvt_pk_bf16_f32 v71, v75, v72
	ds_read_b64_tr_b16 v[72:73], v207 offset:40000
	ds_read_b64_tr_b16 v[76:77], v207 offset:40064
	ds_read_b64_tr_b16 v[130:131], v207 offset:40128
	ds_read_b64_tr_b16 v[74:75], v207 offset:42560
	ds_read_b64_tr_b16 v[78:79], v207 offset:42624
	ds_read_b64_tr_b16 v[132:133], v207 offset:42688
	s_waitcnt lgkmcnt(6)
	v_mfma_f32_32x32x16_bf16 v[48:63], v[64:67], v[68:71], v[48:63]
	s_waitcnt lgkmcnt(2)
	v_mfma_f32_32x32x16_bf16 v[32:47], v[72:75], v[68:71], v[32:47]
	s_waitcnt lgkmcnt(1)
	v_mfma_f32_32x32x16_bf16 v[16:31], v[76:79], v[68:71], v[16:31]
	s_waitcnt lgkmcnt(0)
	v_mfma_f32_32x32x16_bf16 v[0:15], v[130:133], v[68:71], v[0:15]
	s_branch .LBB0_467
.Lsb_near:
	v_add3_u32 v130, s18, v192, v205
	ds_read_b128 v[132:135], v130 offset:8704
	ds_read_b128 v[136:139], v130 offset:8736
	ds_read_b128 v[140:143], v130 offset:8768
	ds_read_b128 v[144:147], v130 offset:8800
	ds_read_b128 v[164:167], v130 offset:8832
	ds_read_b128 v[168:171], v130 offset:8864
	ds_read_b128 v[172:175], v130 offset:8896
	ds_read_b128 v[176:179], v130 offset:8928
	ds_read_b128 v[208:211], v130 offset:224
	v_or_b32_e32 v163, s23, v200
	v_add3_u32 v207, s22, v204, v206
	s_waitcnt lgkmcnt(8)
	v_mfma_f32_32x32x16_bf16 v[66:81], v[132:135], v[82:85], 0
	s_waitcnt lgkmcnt(7)
	v_mfma_f32_32x32x16_bf16 v[66:81], v[136:139], v[86:89], v[66:81]
	s_waitcnt lgkmcnt(6)
	v_mfma_f32_32x32x16_bf16 v[66:81], v[140:143], v[90:93], v[66:81]
	s_waitcnt lgkmcnt(5)
	v_mfma_f32_32x32x16_bf16 v[66:81], v[144:147], v[94:97], v[66:81]
	s_waitcnt lgkmcnt(4)
	v_mfma_f32_32x32x16_bf16 v[66:81], v[164:167], v[98:101], v[66:81]
	s_waitcnt lgkmcnt(3)
	v_mfma_f32_32x32x16_bf16 v[66:81], v[168:171], v[102:105], v[66:81]
	s_waitcnt lgkmcnt(2)
	v_mfma_f32_32x32x16_bf16 v[66:81], v[172:175], v[106:109], v[66:81]
	s_waitcnt lgkmcnt(1)
	v_mfma_f32_32x32x16_bf16 v[66:81], v[176:179], v[110:113], v[66:81]
	s_nop 11
	v_mov_b32_e32 v64, v66
	v_mov_b32_e32 v65, v68
	v_mov_b32_e32 v68, v67
	v_mul_f32_e32 v132, s68, v64
	v_mul_f32_e32 v133, s68, v65
	v_mov_b32_e32 v66, v70
	v_mul_f32_e32 v134, s68, v68
	v_mul_f32_e32 v135, s68, v69
	v_mul_f32_e64 v70, |v132|, s54
	v_mov_b32_e32 v67, v72
	v_mul_f32_e64 v72, |v134|, s54
	v_exp_f32_e32 v70, v70
	v_mul_f32_e64 v131, |v133|, s54
	v_exp_f32_e32 v72, v72
	v_mul_f32_e64 v138, |v135|, s54
	v_exp_f32_e32 v131, v131
	v_mul_f32_e32 v136, s68, v66
	v_mul_f32_e32 v137, s68, v67
	v_exp_f32_e32 v138, v138
	v_mul_f32_e64 v139, |v136|, s54
	v_add_f32_e32 v70, 1.0, v70
	v_exp_f32_e32 v139, v139
	v_add_f32_e32 v72, 1.0, v72
	v_add_f32_e32 v131, 1.0, v131
	v_add_f32_e32 v138, 1.0, v138
	v_log_f32_e32 v70, v70
	v_add_f32_e32 v139, 1.0, v139
	v_log_f32_e32 v72, v72
	v_log_f32_e32 v131, v131
	v_log_f32_e32 v138, v138
	v_mov_b32_e32 v142, v139
	v_mul_f32_e32 v139, 0x3f317217, v70
	v_mul_f32_e32 v140, 0x3f317217, v72
	v_fma_f32 v139, v70, s86, -v139
	v_mul_f32_e32 v141, 0x3f317217, v131
	v_fma_f32 v140, v72, s86, -v140
	v_fmac_f32_e32 v139, 0x3377d1cf, v70
	v_mul_f32_e32 v143, 0x3f317217, v138
	v_fma_f32 v141, v131, s86, -v141
	v_fmac_f32_e32 v140, 0x3377d1cf, v72
	v_fmac_f32_e32 v139, 0x3f317217, v70
	v_fma_f32 v143, v138, s86, -v143
	v_fmac_f32_e32 v141, 0x3377d1cf, v131
	v_fmac_f32_e32 v140, 0x3f317217, v72
	v_fmac_f32_e32 v143, 0x3377d1cf, v138
	v_fmac_f32_e32 v141, 0x3f317217, v131
	v_fmac_f32_e32 v143, 0x3f317217, v138
	v_min_f32_e32 v132, 0, v132
	v_min_f32_e32 v133, 0, v133
	v_sub_f32_e32 v166, v132, v139
	v_sub_f32_e32 v167, v133, v141
	v_fma_f32 v174, -v64, s68, v166
	v_fma_f32 v175, -v65, s68, v167
	v_log_f32_e32 v65, v142
	v_min_f32_e32 v134, 0, v134
	v_min_f32_e32 v135, 0, v135
	v_sub_f32_e32 v164, v134, v140
	v_sub_f32_e32 v165, v135, v143
	v_mov_b32_e32 v72, v71
	v_fma_f32 v172, -v68, s68, v164
	v_fma_f32 v173, -v69, s68, v165
	v_mul_f32_e32 v68, 0x3f317217, v65
	v_fma_f32 v70, v65, s86, -v68
	v_mul_f32_e32 v68, s68, v72
	v_mul_f32_e32 v69, s68, v73
	v_fmac_f32_e32 v70, 0x3377d1cf, v65
	v_mul_f32_e64 v71, |v68|, s54
	v_exp_f32_e32 v71, v71
	v_fmac_f32_e32 v70, 0x3f317217, v65
	v_mul_f32_e64 v131, |v137|, s54
	v_exp_f32_e32 v131, v131
	v_mov_b32_e32 v65, v70
	v_add_f32_e32 v70, 1.0, v71
	v_mul_f32_e64 v133, |v69|, s54
	v_exp_f32_e32 v133, v133
	v_log_f32_e32 v71, v70
	v_mov_b32_e32 v70, v65
	v_min_f32_e32 v64, 0, v136
	v_mul_f32_e32 v65, 0x3f317217, v71
	v_fma_f32 v65, v71, s86, -v65
	v_fmac_f32_e32 v65, 0x3377d1cf, v71
	v_fmac_f32_e32 v65, 0x3f317217, v71
	v_min_f32_e32 v68, 0, v68
	v_min_f32_e32 v69, 0, v69
	v_add_f32_e32 v71, 1.0, v131
	v_mov_b32_e32 v140, v78
	v_mov_b32_e32 v141, v80
	v_log_f32_e32 v71, v71
	v_mov_b32_e32 v132, v65
	v_min_f32_e32 v65, 0, v137
	v_mul_f32_e32 v131, 0x3f317217, v71
	v_fma_f32 v131, v71, s86, -v131
	v_fmac_f32_e32 v131, 0x3377d1cf, v71
	v_fmac_f32_e32 v131, 0x3f317217, v71
	v_mul_f32_e32 v142, s68, v140
	v_mul_f32_e32 v143, s68, v141
	v_mov_b32_e32 v80, v79
	v_mov_b32_e32 v71, v131
	v_add_f32_e32 v131, 1.0, v133
	v_sub_f32_e32 v168, v64, v70
	v_sub_f32_e32 v169, v65, v71
	v_log_f32_e32 v131, v131
	v_fma_f32 v176, -v66, s68, v168
	v_fma_f32 v177, -v67, s68, v169
	v_mul_f32_e32 v144, s68, v80
	v_mul_f32_e32 v145, s68, v81
	v_mul_f32_e32 v64, 0x3f317217, v131
	v_fma_f32 v70, v131, s86, -v64
	v_mov_b32_e32 v64, v74
	v_mul_f32_e32 v66, s68, v64
	v_mul_f32_e32 v67, s68, v76
	v_fmac_f32_e32 v70, 0x3377d1cf, v131
	v_mul_f32_e64 v71, |v66|, s54
	v_exp_f32_e32 v71, v71
	v_fmac_f32_e32 v70, 0x3f317217, v131
	v_min_f32_e32 v66, 0, v66
	v_mov_b32_e32 v133, v70
	v_add_f32_e32 v70, 1.0, v71
	v_sub_f32_e32 v170, v68, v132
	v_sub_f32_e32 v171, v69, v133
	ds_read_b128 v[132:135], v130 offset:32
	v_log_f32_e32 v70, v70
	v_fma_f32 v178, -v72, s68, v170
	v_fma_f32 v179, -v73, s68, v171
	v_mul_f32_e64 v73, |v67|, s54
	v_exp_f32_e32 v73, v73
	v_mul_f32_e32 v68, 0x3f317217, v70
	v_fma_f32 v71, v70, s86, -v68
	v_mul_f32_e32 v68, s68, v75
	v_mul_f32_e32 v69, s68, v77
	v_fmac_f32_e32 v71, 0x3377d1cf, v70
	v_mul_f32_e64 v72, |v68|, s54
	v_exp_f32_e32 v72, v72
	v_fmac_f32_e32 v71, 0x3f317217, v70
	v_mul_f32_e64 v74, |v69|, s54
	v_exp_f32_e32 v74, v74
	v_mov_b32_e32 v70, v71
	v_add_f32_e32 v71, 1.0, v72
	v_min_f32_e32 v67, 0, v67
	v_min_f32_e32 v68, 0, v68
	v_log_f32_e32 v71, v71
	v_min_f32_e32 v69, 0, v69
	v_mul_f32_e32 v72, 0x3f317217, v71
	v_fma_f32 v72, v71, s86, -v72
	v_fmac_f32_e32 v72, 0x3377d1cf, v71
	v_fmac_f32_e32 v72, 0x3f317217, v71
	s_nop 1
	v_mov_b32_e32 v71, v72
	v_add_f32_e32 v72, 1.0, v73
	s_nop 1
	v_log_f32_e32 v73, v72
	v_mov_b32_e32 v72, v71
	v_mul_f32_e32 v71, 0x3f317217, v73
	v_fma_f32 v71, v73, s86, -v71
	v_fmac_f32_e32 v71, 0x3377d1cf, v73
	v_fmac_f32_e32 v71, 0x3f317217, v73
	s_nop 1
	v_add_f32_e32 v73, 1.0, v74
	v_sub_f32_e32 v180, v66, v70
	v_sub_f32_e32 v181, v67, v71
	v_mul_f32_e64 v70, |v143|, s54
	v_log_f32_e32 v73, v73
	v_fma_f32 v184, -v64, s68, v180
	v_fma_f32 v185, -v76, s68, v181
	v_mul_f32_e64 v65, |v142|, s54
	v_exp_f32_e32 v65, v65
	v_mul_f32_e32 v64, 0x3f317217, v73
	v_fma_f32 v64, v73, s86, -v64
	v_fmac_f32_e32 v64, 0x3377d1cf, v73
	v_fmac_f32_e32 v64, 0x3f317217, v73
	v_exp_f32_e32 v131, v70
	v_mov_b32_e32 v73, v64
	v_add_f32_e32 v64, 1.0, v65
	v_mul_f32_e64 v66, |v144|, s54
	v_exp_f32_e32 v66, v66
	v_log_f32_e32 v64, v64
	v_sub_f32_e32 v182, v68, v72
	v_sub_f32_e32 v183, v69, v73
	v_add_f32_e32 v131, 1.0, v131
	v_fma_f32 v186, -v75, s68, v182
	v_fma_f32 v187, -v77, s68, v183
	v_mul_f32_e32 v65, 0x3f317217, v64
	v_fma_f32 v65, v64, s86, -v65
	v_fmac_f32_e32 v65, 0x3377d1cf, v64
	v_fmac_f32_e32 v65, 0x3f317217, v64
	v_min_f32_e32 v142, 0, v142
	v_min_f32_e32 v143, 0, v143
	v_mov_b32_e32 v64, v65
	v_add_f32_e32 v65, 1.0, v66
	v_min_f32_e32 v144, 0, v144
	v_log_f32_e32 v68, v65
	v_mov_b32_e32 v146, v64
	ds_read_b128 v[64:67], v130
	v_mul_f32_e32 v69, 0x3f317217, v68
	v_fma_f32 v69, v68, s86, -v69
	v_fmac_f32_e32 v69, 0x3377d1cf, v68
	v_fmac_f32_e32 v69, 0x3f317217, v68
	s_nop 0
	v_mov_b32_e32 v147, v69
	s_waitcnt lgkmcnt(0)
	v_mfma_f32_32x32x16_bf16 v[64:79], v[64:67], v[82:85], 0
	v_mov_b32_e32 v148, v147
	s_nop 0
	ds_read_b128 v[136:139], v130 offset:64
	v_log_f32_e32 v131, v131
	v_mfma_f32_32x32x16_bf16 v[64:79], v[132:135], v[86:89], v[64:79]
	v_mul_f32_e32 v132, 0x3f317217, v131
	v_fma_f32 v147, v131, s86, -v132
	ds_read_b128 v[132:135], v130 offset:96
	v_fmac_f32_e32 v147, 0x3377d1cf, v131
	v_fmac_f32_e32 v147, 0x3f317217, v131
	s_waitcnt lgkmcnt(1)
	v_mfma_f32_32x32x16_bf16 v[64:79], v[136:139], v[90:93], v[64:79]
	v_mul_f32_e64 v137, |v145|, s54
	v_exp_f32_e32 v149, v137
	ds_read_b128 v[136:139], v130 offset:128
	s_waitcnt lgkmcnt(1)
	v_mfma_f32_32x32x16_bf16 v[64:79], v[132:135], v[94:97], v[64:79]
	v_add_f32_e32 v131, 1.0, v149
	v_add_f32_e64 v188, v142, -v146
	v_add_f32_e64 v189, v143, -v147
	v_min_f32_e32 v145, 0, v145
	ds_read_b128 v[132:135], v130 offset:160
	s_waitcnt lgkmcnt(1)
	v_mfma_f32_32x32x16_bf16 v[64:79], v[136:139], v[98:101], v[64:79]
	v_log_f32_e32 v131, v131
	v_fma_f32 v212, -v140, s68, v188
	v_fma_f32 v213, -v141, s68, v189
	v_mul_f32_e32 v136, 0x3f317217, v131
	v_fma_f32 v140, v131, s86, -v136
	ds_read_b128 v[136:139], v130 offset:192
	s_waitcnt lgkmcnt(1)
	v_mfma_f32_32x32x16_bf16 v[64:79], v[132:135], v[102:105], v[64:79]
	v_fmac_f32_e32 v140, 0x3377d1cf, v131
	v_fmac_f32_e32 v140, 0x3f317217, v131
	s_nop 0
	s_waitcnt lgkmcnt(0)
	v_mfma_f32_32x32x16_bf16 v[64:79], v[136:139], v[106:109], v[64:79]
	v_add_f32_e64 v190, v144, -v148
	v_add_f32_e64 v191, v145, -v140
	ds_read_b64_tr_b16 v[146:147], v207 offset:45056
	ds_read_b64_tr_b16 v[142:143], v207 offset:45120
	ds_read_b64_tr_b16 v[138:139], v207 offset:45184
	ds_read_b64_tr_b16 v[134:135], v207 offset:45248
	ds_read_b64_tr_b16 v[148:149], v207 offset:47616
	ds_read_b64_tr_b16 v[144:145], v207 offset:47680
	ds_read_b64_tr_b16 v[140:141], v207 offset:47744
	ds_read_b64_tr_b16 v[136:137], v207 offset:47808
	ds_read_b64_tr_b16 v[130:131], v207 offset:50176
	ds_read_b64_tr_b16 v[132:133], v207 offset:52736
	v_fma_f32 v216, -v80, s68, v190
	v_fma_f32 v217, -v81, s68, v191
	v_or_b32_e32 v80, 34, v163
	v_cmp_lt_i32_e64 s[26:27], v80, v153
	v_mfma_f32_32x32x16_bf16 v[64:79], v[208:211], v[110:113], v[64:79]
	v_or_b32_e32 v208, 32, v163
	v_cmp_lt_i32_e64 s[30:31], v208, v152
	v_or_b32_e32 v208, 33, v163
	v_cmp_lt_i32_e64 s[40:41], v208, v152
	v_cndmask_b32_e64 v80, 0, v174, s[30:31]
	v_or_b32_e32 v174, 35, v163
	v_cmp_lt_i32_e64 s[38:39], v174, v153
	v_cndmask_b32_e64 v81, 0, v175, s[26:27]
	v_cndmask_b32_e64 v174, 0, v172, s[40:41]
	v_cndmask_b32_e64 v175, 0, v173, s[38:39]
	v_add_f32_e32 v80, v80, v174
	v_add_f32_e32 v81, v81, v175
	v_or_b32_e32 v208, 40, v163
	v_add_f32_e32 v172, v80, v81
	v_add_f32_e32 v173, v81, v80
	v_cmp_lt_i32_e64 s[22:23], v208, v152
	v_or_b32_e32 v173, 42, v163
	v_cmp_lt_i32_e64 s[18:19], v173, v153
	v_or_b32_e32 v173, 43, v163
	v_or_b32_e32 v208, 41, v163
	v_cmp_lt_i32_e64 s[28:29], v173, v153
	v_or_b32_e32 v173, 50, v163
	v_cmp_lt_i32_e64 s[34:35], v208, v152
	v_or_b32_e32 v208, 48, v163
	v_cmp_lt_i32_e32 vcc, v173, v153
	v_or_b32_e32 v173, 51, v163
	v_cmp_lt_i32_e64 s[42:43], v208, v152
	v_or_b32_e32 v208, 49, v163
	v_cmp_lt_i32_e64 s[16:17], v173, v153
	v_or_b32_e32 v173, 58, v163
	v_cmp_lt_i32_e64 s[44:45], v208, v152
	v_or_b32_e32 v208, 56, v163
	v_cmp_lt_i32_e64 s[14:15], v173, v153
	v_or_b32_e32 v173, 59, v163
	v_or_b32_e32 v210, 57, v163
	v_cmp_lt_i32_e64 s[36:37], v208, v152
	v_cmp_lt_i32_e64 s[20:21], v173, v153
	v_cmp_lt_i32_e64 s[24:25], v210, v152
	v_cndmask_b32_e32 v185, 0, v185, vcc
	v_cndmask_b32_e64 v184, 0, v184, s[42:43]
	v_cndmask_b32_e64 v187, 0, v187, s[16:17]
	v_cndmask_b32_e64 v186, 0, v186, s[44:45]
	v_cndmask_b32_e64 v209, 0, v213, s[14:15]
	v_cndmask_b32_e64 v208, 0, v212, s[36:37]
	v_cndmask_b32_e64 v211, 0, v217, s[20:21]
	v_cndmask_b32_e64 v210, 0, v216, s[24:25]
	v_add_f32_e32 v184, v184, v186
	v_add_f32_e32 v185, v185, v187
	v_add_f32_e32 v208, v208, v210
	v_add_f32_e32 v209, v209, v211
	v_add_f32_e32 v240, v184, v185
	v_add_f32_e32 v241, v185, v184
	v_add_f32_e32 v212, v208, v209
	v_add_f32_e32 v213, v209, v208
	s_waitcnt lgkmcnt(0)
	v_mov_b32_e32 v216, v212
	v_mov_b32_e32 v184, v240
	v_mov_b32_e32 v248, v212
	v_mov_b32_e32 v249, v240
	s_nop 0
	v_permlane32_swap_b32_e32 v248, v216
	v_permlane32_swap_b32_e32 v249, v184
	v_cndmask_b32_e64 v216, v248, v216, s[10:11]
	v_cndmask_b32_e64 v184, v249, v184, s[10:11]
	v_cndmask_b32_e64 v177, 0, v177, s[18:19]
	v_add_f32_e32 v208, v212, v216
	v_cndmask_b32_e64 v213, 0, v184, s[10:11]
	v_add_f32_e32 v208, v213, v208
	v_add_f32_e32 v245, v162, v208
	v_add_f32_e32 v246, v186, v185
	v_add_f32_e32 v247, v180, v245
	v_add_f32_e32 v182, v182, v245
	v_add_f32_e32 v180, v246, v247
	v_mul_f32_e32 v180, 0x3fb8aa3b, v180
	v_exp_f32_e32 v180, v180
	v_add_f32_e32 v182, v185, v182
	v_mul_f32_e32 v182, 0x3fb8aa3b, v182
	v_cndmask_b32_e64 v176, 0, v176, s[22:23]
	v_cndmask_b32_e64 v179, 0, v179, s[28:29]
	v_cndmask_b32_e64 v178, 0, v178, s[34:35]
	v_exp_f32_e32 v182, v182
	v_add_f32_e32 v176, v176, v178
	v_add_f32_e32 v177, v177, v179
	v_cndmask_b32_e64 v213, 0, v180, s[42:43]
	v_add_f32_e32 v180, v181, v245
	v_add_f32_e32 v242, v176, v177
	v_add_f32_e32 v243, v177, v176
	v_add_f32_e32 v180, v187, v180
	ds_bpermute_b32 v80, v235, v172
	ds_bpermute_b32 v176, v235, v242
	v_mul_f32_e32 v180, 0x3fb8aa3b, v180
	v_cndmask_b32_e64 v215, 0, v182, s[44:45]
	v_exp_f32_e32 v239, v180
	v_add_f32_e32 v180, v183, v245
	v_add_f32_e32 v182, v184, v216
	v_add_f32_e32 v183, v240, v212
	v_add_f32_e32 v180, 0, v180
	v_add_f32_e32 v181, v242, v183
	v_add_f32_e32 v181, v181, v216
	v_add_f32_e32 v181, v181, v184
	v_cndmask_b32_e64 v173, 0, v216, s[10:11]
	s_waitcnt lgkmcnt(1)
	v_cndmask_b32_e64 v208, 0, v80, s[10:11]
	v_mul_f32_e32 v180, 0x3fb8aa3b, v180
	s_waitcnt lgkmcnt(0)
	v_add_f32_e32 v181, v181, v176
	v_exp_f32_e32 v241, v180
	v_add_f32_e32 v180, v162, v173
	v_add_f32_e32 v173, v183, v216
	v_add_f32_e32 v181, v208, v181
	v_cndmask_b32_e64 v186, 0, v176, s[10:11]
	v_add_f32_e32 v173, v173, v184
	v_add_f32_e32 v185, v162, v181
	v_add_f32_e32 v173, v186, v173
	v_add_f32_e32 v164, v164, v185
	v_add_f32_e32 v186, v174, v81
	v_add_f32_e32 v187, v166, v185
	v_add_f32_e32 v81, v81, v164
	v_add_f32_e32 v164, v167, v185
	v_add_f32_e32 v165, v165, v185
	v_add_f32_e32 v166, v186, v187
	v_add_f32_e32 v164, v175, v164
	v_add_f32_e32 v165, 0, v165
	v_mul_f32_e32 v166, 0x3fb8aa3b, v166
	v_mul_f32_e32 v164, 0x3fb8aa3b, v164
	v_mul_f32_e32 v165, 0x3fb8aa3b, v165
	v_exp_f32_e32 v166, v166
	v_exp_f32_e32 v164, v164
	v_exp_f32_e32 v165, v165
	v_cndmask_b32_e64 v174, 0, v166, s[30:31]
	v_cndmask_b32_e64 v175, 0, v164, s[26:27]
	v_cndmask_b32_e64 v181, 0, v165, s[38:39]
	v_add_f32_e32 v165, v162, v173
	v_add_f32_e32 v166, v178, v177
	v_add_f32_e32 v167, v168, v165
	v_mul_f32_e32 v81, 0x3fb8aa3b, v81
	v_add_f32_e32 v164, v166, v167
	v_add_f32_e32 v166, v170, v165
	v_add_f32_e32 v167, v169, v165
	v_add_f32_e32 v165, v171, v165
	v_add_f32_e32 v166, v177, v166
	v_add_f32_e32 v167, v179, v167
	v_add_f32_e32 v165, 0, v165
	v_mul_f32_e32 v164, 0x3fb8aa3b, v164
	v_mul_f32_e32 v166, 0x3fb8aa3b, v166
	v_mul_f32_e32 v167, 0x3fb8aa3b, v167
	v_mul_f32_e32 v165, 0x3fb8aa3b, v165
	v_exp_f32_e32 v81, v81
	v_exp_f32_e32 v164, v164
	v_exp_f32_e32 v166, v166
	v_exp_f32_e32 v167, v167
	v_exp_f32_e32 v165, v165
	v_cndmask_b32_e64 v81, 0, v81, s[40:41]
	v_cndmask_b32_e64 v168, 0, v164, s[22:23]
	v_cndmask_b32_e64 v166, 0, v166, s[34:35]
	v_cndmask_b32_e64 v167, 0, v167, s[18:19]
	v_cndmask_b32_e64 v169, 0, v165, s[28:29]
	v_cvt_pk_bf16_f32 v164, v174, v81
	v_cvt_pk_bf16_f32 v165, v175, v181
	v_cvt_pk_bf16_f32 v166, v168, v166
	v_cvt_pk_bf16_f32 v167, v167, v169
	s_nop 0
	s_nop 0
	v_mfma_f32_32x32x16_bf16 v[48:63], v[146:149], v[164:167], v[48:63]
	v_add_f32_e64 v146, v180, v188
	v_add_f32_e64 v147, v210, v209
	v_add_f32_e32 v81, v146, v147
	v_mul_f32_e32 v81, 0x3fb8aa3b, v81
	v_exp_f32_e32 v81, v81
	v_cndmask_b32_e32 v146, 0, v239, vcc
	v_cndmask_b32_e64 v81, 0, v81, s[36:37]
	v_mfma_f32_32x32x16_bf16 v[32:47], v[142:145], v[164:167], v[32:47]
	v_add_f32_e32 v143, v180, v190
	v_add_f32_e32 v144, v180, v189
	v_add_f32_e32 v143, v143, v209
	v_mul_f32_e32 v143, 0x3fb8aa3b, v143
	v_exp_f32_e32 v143, v143
	v_cndmask_b32_e64 v142, 0, v241, s[16:17]
	v_mfma_f32_32x32x16_bf16 v[16:31], v[138:141], v[164:167], v[16:31]
	v_add_f32_e32 v139, v180, v191
	v_add_f32_e32 v138, v144, v211
	v_add_f32_e32 v139, 0, v139
	v_mul_f32_e32 v138, 0x3fb8aa3b, v138
	v_mul_f32_e32 v139, 0x3fb8aa3b, v139
	v_exp_f32_e32 v138, v138
	v_exp_f32_e32 v139, v139
	v_mfma_f32_32x32x16_bf16 v[0:15], v[134:137], v[164:167], v[0:15]
	v_cndmask_b32_e64 v136, 0, v143, s[24:25]
	v_cndmask_b32_e64 v137, 0, v138, s[14:15]
	v_cndmask_b32_e64 v138, 0, v139, s[20:21]
	v_cvt_pk_bf16_f32 v134, v213, v215
	v_cvt_pk_bf16_f32 v135, v146, v142
	v_cvt_pk_bf16_f32 v136, v81, v136
	v_cvt_pk_bf16_f32 v137, v137, v138
	ds_read_b64_tr_b16 v[138:139], v207 offset:50240
	ds_read_b64_tr_b16 v[142:143], v207 offset:50304
	ds_read_b64_tr_b16 v[146:147], v207 offset:50368
	ds_read_b64_tr_b16 v[140:141], v207 offset:52800
	ds_read_b64_tr_b16 v[144:145], v207 offset:52864
	ds_read_b64_tr_b16 v[148:149], v207 offset:52928
	v_mfma_f32_32x32x16_bf16 v[48:63], v[130:133], v[134:137], v[48:63]
	v_mov_b32_e32 v130, v64
	v_mov_b32_e32 v131, v68
	v_mul_f32_e64 v132, v130, s68
	v_mul_f32_e64 v133, v131, s68
	v_mul_f32_e64 v64, |v132|, s54
	v_exp_f32_e32 v64, v64
	v_add_f32_e32 v80, v80, v176
	v_add_f32_e32 v81, v172, v242
	s_waitcnt lgkmcnt(2)
	v_mfma_f32_32x32x16_bf16 v[32:47], v[138:141], v[134:137], v[32:47]
	v_add_f32_e64 v80, v80, v182
	v_add_f32_e64 v81, v81, v183
	v_add_f32_e32 v64, 1.0, v64
	s_nop 1
	v_log_f32_e32 v138, v64
	v_min_f32_e32 v64, 0, v132
	s_waitcnt lgkmcnt(1)
	v_mfma_f32_32x32x16_bf16 v[16:31], v[142:145], v[134:137], v[16:31]
	v_mul_f32_e64 v143, |v133|, s54
	v_mul_f32_e32 v68, 0x3f317217, v138
	v_fma_f32 v132, v138, s86, -v68
	v_mov_b32_e32 v68, v65
	v_fmac_f32_e32 v132, 0x3377d1cf, v138
	v_fmac_f32_e32 v132, 0x3f317217, v138
	s_waitcnt lgkmcnt(0)
	v_mfma_f32_32x32x16_bf16 v[0:15], v[146:149], v[134:137], v[0:15]
	v_mul_f32_e64 v134, v68, s68
	v_mul_f32_e64 v135, v69, s68
	v_mul_f32_e64 v65, |v134|, s54
	v_exp_f32_e32 v65, v65
	v_mov_b32_e32 v137, v70
	v_exp_f32_e32 v143, v143
	v_min_f32_e32 v134, 0, v134
	v_add_f32_e32 v65, 1.0, v65
	v_add_f32_e32 v143, 1.0, v143
	s_nop 0
	v_log_f32_e32 v65, v65
	s_nop 0
	v_mul_f32_e32 v136, 0x3f317217, v65
	v_fma_f32 v140, v65, s86, -v136
	v_mov_b32_e32 v136, v66
	v_mul_f32_e32 v138, s68, v136
	v_mul_f32_e32 v139, s68, v137
	v_fmac_f32_e32 v140, 0x3377d1cf, v65
	v_mul_f32_e64 v66, |v138|, s54
	v_exp_f32_e32 v66, v66
	v_fmac_f32_e32 v140, 0x3f317217, v65
	v_min_f32_e32 v138, 0, v138
	v_add_f32_e32 v66, 1.0, v66
	v_mov_b32_e32 v65, v140
	s_nop 1
	v_log_f32_e32 v142, v66
	v_mov_b32_e32 v70, v67
	v_mul_f32_e32 v140, s68, v70
	v_mul_f32_e32 v141, s68, v71
	v_mul_f32_e64 v67, |v140|, s54
	v_exp_f32_e32 v67, v67
	v_mov_b32_e32 v66, v65
	v_mul_f32_e32 v65, 0x3f317217, v142
	v_fma_f32 v65, v142, s86, -v65
	v_fmac_f32_e32 v65, 0x3377d1cf, v142
	v_fmac_f32_e32 v65, 0x3f317217, v142
	v_add_f32_e32 v67, 1.0, v67
	v_min_f32_e32 v140, 0, v140
	s_nop 1
	v_log_f32_e32 v67, v67
	v_mov_b32_e32 v142, v65
	v_mul_f32_e32 v65, 0x3f317217, v67
	v_fma_f32 v65, v67, s86, -v65
	v_fmac_f32_e32 v65, 0x3377d1cf, v67
	v_fmac_f32_e32 v65, 0x3f317217, v67
	s_nop 1
	s_nop 0
	v_log_f32_e32 v143, v143
	v_mov_b32_e32 v144, v65
	v_min_f32_e32 v65, 0, v133
	v_or_b32_e32 v67, 8, v163
	v_mul_f32_e32 v133, 0x3f317217, v143
	v_fma_f32 v133, v143, s86, -v133
	v_fmac_f32_e32 v133, 0x3377d1cf, v143
	v_fmac_f32_e32 v133, 0x3f317217, v143
	s_nop 1
	v_sub_f32_e32 v64, v64, v132
	v_sub_f32_e32 v65, v65, v133
	v_mul_f32_e64 v132, |v135|, s54
	v_exp_f32_e32 v132, v132
	v_cmp_lt_i32_e32 vcc, v67, v153
	v_fma_f32 v130, -v130, s68, v64
	v_fma_f32 v131, -v131, s68, v65
	v_cmp_lt_i32_e64 s[14:15], v163, v152
	v_add_f32_e32 v67, 1.0, v132
	s_nop 0
	v_cndmask_b32_e64 v146, 0, v130, s[14:15]
	v_min_f32_e32 v135, 0, v135
	v_log_f32_e32 v67, v67
	v_cndmask_b32_e32 v147, 0, v131, vcc
	v_or_b32_e32 v131, 1, v163
	v_or_b32_e32 v130, 9, v163
	v_mul_f32_e32 v132, 0x3f317217, v67
	v_fma_f32 v132, v67, s86, -v132
	v_fmac_f32_e32 v132, 0x3377d1cf, v67
	v_fmac_f32_e32 v132, 0x3f317217, v67
	s_nop 1
	v_mov_b32_e32 v67, v132
	v_mul_f32_e64 v132, |v139|, s54
	v_sub_f32_e32 v66, v134, v66
	v_sub_f32_e32 v67, v135, v67
	v_exp_f32_e32 v134, v132
	v_fma_f32 v68, -v68, s68, v66
	v_fma_f32 v69, -v69, s68, v67
	v_cmp_lt_i32_e64 s[18:19], v131, v152
	v_cmp_lt_i32_e64 s[16:17], v130, v153
	v_min_f32_e32 v139, 0, v139
	v_cndmask_b32_e64 v132, 0, v68, s[18:19]
	v_add_f32_e32 v68, 1.0, v134
	v_cndmask_b32_e64 v133, 0, v69, s[16:17]
	v_or_b32_e32 v135, 2, v163
	v_log_f32_e32 v68, v68
	v_cmp_lt_i32_e64 s[24:25], v135, v152
	v_or_b32_e32 v134, 10, v163
	v_mul_f32_e32 v69, 0x3f317217, v68
	v_fma_f32 v69, v68, s86, -v69
	v_fmac_f32_e32 v69, 0x3377d1cf, v68
	v_fmac_f32_e32 v69, 0x3f317217, v68
	s_nop 1
	v_sub_f32_e32 v68, v138, v142
	v_sub_f32_e32 v69, v139, v69
	v_cmp_lt_i32_e64 s[22:23], v134, v153
	v_fma_f32 v130, -v136, s68, v68
	v_fma_f32 v131, -v137, s68, v69
	v_mul_f32_e64 v136, |v141|, s54
	v_exp_f32_e32 v136, v136
	v_cndmask_b32_e64 v142, 0, v130, s[24:25]
	v_cndmask_b32_e64 v143, 0, v131, s[22:23]
	v_mul_f32_e32 v134, s68, v72
	v_mul_f32_e32 v135, s68, v73
	v_add_f32_e32 v130, 1.0, v136
	v_mul_f32_e64 v138, |v134|, s54
	v_exp_f32_e32 v138, v138
	v_log_f32_e32 v130, v130
	v_or_b32_e32 v136, 11, v163
	v_or_b32_e32 v137, 3, v163
	v_cmp_lt_i32_e64 s[34:35], v137, v152
	v_mul_f32_e32 v131, 0x3f317217, v130
	v_fma_f32 v131, v130, s86, -v131
	v_fmac_f32_e32 v131, 0x3377d1cf, v130
	v_fmac_f32_e32 v131, 0x3f317217, v130
	v_min_f32_e32 v134, 0, v134
	v_min_f32_e32 v141, 0, v141
	v_cmp_lt_i32_e64 s[26:27], v136, v153
	v_add_f32_e32 v136, 1.0, v138
	v_sub_f32_e32 v130, v140, v144
	v_sub_f32_e32 v131, v141, v131
	v_log_f32_e32 v136, v136
	v_mul_f32_e64 v138, |v135|, s54
	v_exp_f32_e32 v138, v138
	v_min_f32_e32 v135, 0, v135
	v_mul_f32_e32 v137, 0x3f317217, v136
	v_fma_f32 v137, v136, s86, -v137
	v_fmac_f32_e32 v137, 0x3377d1cf, v136
	v_fmac_f32_e32 v137, 0x3f317217, v136
	v_or_b32_e32 v140, 16, v163
	v_cmp_lt_i32_e64 s[36:37], v140, v152
	v_mov_b32_e32 v136, v137
	v_add_f32_e32 v137, 1.0, v138
	v_fma_f32 v70, -v70, s68, v130
	v_fma_f32 v71, -v71, s68, v131
	s_nop 0
	v_log_f32_e32 v137, v137
	v_cndmask_b32_e64 v71, 0, v71, s[26:27]
	v_mul_f32_e32 v138, 0x3f317217, v137
	v_fma_f32 v138, v137, s86, -v138
	v_fmac_f32_e32 v138, 0x3377d1cf, v137
	v_fmac_f32_e32 v138, 0x3f317217, v137
	v_cndmask_b32_e64 v70, 0, v70, s[34:35]
	s_nop 0
	v_sub_f32_e32 v134, v134, v136
	v_sub_f32_e32 v135, v135, v138
	v_mul_f32_e32 v136, s68, v74
	v_mul_f32_e32 v137, s68, v75
	v_or_b32_e32 v138, 17, v163
	v_mul_f32_e64 v139, |v136|, s54
	v_exp_f32_e32 v139, v139
	v_cmp_lt_i32_e64 s[20:21], v138, v153
	v_mul_f32_e64 v140, |v137|, s54
	v_exp_f32_e32 v140, v140
	v_add_f32_e32 v138, 1.0, v139
	v_min_f32_e32 v136, 0, v136
	v_min_f32_e32 v137, 0, v137
	v_log_f32_e32 v138, v138
	v_fma_f32 v72, -v72, s68, v134
	v_fma_f32 v73, -v73, s68, v135
	v_mul_f32_e32 v139, 0x3f317217, v138
	v_fma_f32 v139, v138, s86, -v139
	v_fmac_f32_e32 v139, 0x3377d1cf, v138
	v_fmac_f32_e32 v139, 0x3f317217, v138
	v_cndmask_b32_e64 v73, 0, v73, s[20:21]
	v_cndmask_b32_e64 v72, 0, v72, s[36:37]
	v_mov_b32_e32 v138, v139
	v_add_f32_e32 v139, 1.0, v140
	s_nop 1
	v_log_f32_e32 v139, v139
	s_nop 0
	v_mul_f32_e32 v140, 0x3f317217, v139
	v_fma_f32 v140, v139, s86, -v140
	v_fmac_f32_e32 v140, 0x3377d1cf, v139
	v_fmac_f32_e32 v140, 0x3f317217, v139
	s_nop 1
	v_mov_b32_e32 v139, v140
	v_or_b32_e32 v140, 18, v163
	v_cmp_lt_i32_e64 s[30:31], v140, v152
	v_add_f32_e32 v140, v142, v70
	v_add_f32_e32 v141, v143, v71
	v_mov_b32_e32 v142, v76
	v_mov_b32_e32 v143, v78
	v_mul_f32_e32 v144, s68, v142
	v_mul_f32_e32 v145, s68, v143
	v_sub_f32_e32 v136, v136, v138
	v_sub_f32_e32 v137, v137, v139
	v_mul_f32_e64 v76, |v144|, s54
	v_exp_f32_e32 v78, v76
	v_or_b32_e32 v138, 19, v163
	v_fma_f32 v74, -v74, s68, v136
	v_fma_f32 v75, -v75, s68, v137
	v_cmp_lt_i32_e64 s[28:29], v138, v153
	v_cndmask_b32_e64 v138, 0, v74, s[30:31]
	v_mul_f32_e64 v149, |v145|, s54
	v_cndmask_b32_e64 v139, 0, v75, s[28:29]
	v_add_f32_e32 v74, v146, v132
	v_add_f32_e32 v75, v147, v133
	v_exp_f32_e32 v149, v149
	v_add_f32_e32 v146, v74, v140
	v_add_f32_e32 v147, v75, v141
	v_add_f32_e32 v74, 1.0, v78
	ds_bpermute_b32 v148, v235, v147
	ds_bpermute_b32 v76, v235, v146
	v_log_f32_e32 v75, v74
	s_nop 0
	v_mul_f32_e32 v78, 0x3f317217, v75
	v_add_f32_e32 v164, v72, v73
	v_add_f32_e32 v165, v73, v75
	v_min_f32_e32 v74, 0, v144
	v_fma_f32 v144, v75, s86, -v78
	v_mov_b32_e32 v78, v77
	v_mul_f32_e32 v166, s68, v78
	v_mul_f32_e32 v167, s68, v79
	v_fmac_f32_e32 v144, 0x3377d1cf, v75
	v_mul_f32_e64 v77, |v166|, s54
	v_exp_f32_e32 v77, v77
	v_fmac_f32_e32 v144, 0x3f317217, v75
	v_min_f32_e32 v166, 0, v166
	v_add_f32_e32 v77, 1.0, v77
	v_or_b32_e32 v165, 24, v163
	v_cmp_lt_i32_e64 s[42:43], v165, v152
	v_log_f32_e32 v77, v77
	v_mov_b32_e32 v144, v144
	v_mul_f32_e32 v75, 0x3f317217, v77
	v_fma_f32 v75, v77, s86, -v75
	v_fmac_f32_e32 v75, 0x3377d1cf, v77
	v_fmac_f32_e32 v75, 0x3f317217, v77
	s_nop 1
	v_mov_b32_e32 v168, v75
	v_add_f32_e32 v75, 1.0, v149
	v_or_b32_e32 v149, 26, v163
	s_nop 0
	v_log_f32_e32 v77, v75
	v_min_f32_e32 v75, 0, v145
	v_mul_f32_e32 v145, 0x3f317217, v77
	v_fma_f32 v145, v77, s86, -v145
	v_fmac_f32_e32 v145, 0x3377d1cf, v77
	v_fmac_f32_e32 v145, 0x3f317217, v77
	s_nop 1
	v_mov_b32_e32 v145, v145
	v_mul_f32_e64 v77, |v167|, s54
	v_exp_f32_e32 v77, v77
	v_sub_f32_e32 v74, v74, v144
	v_sub_f32_e32 v75, v75, v145
	v_min_f32_e32 v167, 0, v167
	v_cmp_lt_i32_e64 s[38:39], v149, v153
	v_add_f32_e32 v77, 1.0, v77
	v_or_b32_e32 v149, 27, v163
	v_or_b32_e32 v163, 25, v163
	v_log_f32_e32 v77, v77
	v_fma_f32 v142, -v142, s68, v74
	v_fma_f32 v143, -v143, s68, v75
	v_mul_f32_e32 v144, 0x3f317217, v77
	v_fma_f32 v144, v77, s86, -v144
	v_fmac_f32_e32 v144, 0x3377d1cf, v77
	v_fmac_f32_e32 v144, 0x3f317217, v77
	v_cndmask_b32_e64 v143, 0, v143, s[38:39]
	v_cndmask_b32_e64 v142, 0, v142, s[42:43]
	v_mov_b32_e32 v169, v144
	v_sub_f32_e32 v144, v166, v168
	v_sub_f32_e32 v145, v167, v169
	v_cmp_lt_i32_e64 s[40:41], v149, v153
	v_fma_f32 v78, -v78, s68, v144
	v_fma_f32 v79, -v79, s68, v145
	v_cmp_lt_i32_e64 s[44:45], v163, v152
	v_cndmask_b32_e64 v167, 0, v79, s[40:41]
	v_mov_b32_e32 v168, v132
	v_cndmask_b32_e64 v166, 0, v78, s[44:45]
	v_add_f32_e32 v142, v142, v166
	v_add_f32_e32 v143, v143, v167
	v_add_f32_e32 v170, v138, v139
	v_add_f32_e32 v171, v139, v133
	v_add_f32_e32 v164, v164, v170
	v_add_f32_e32 v165, v142, v143
	ds_bpermute_b32 v149, v235, v165
	ds_bpermute_b32 v77, v235, v164
	v_add_f32_e32 v78, v146, v146
	v_add_f32_e32 v79, v146, v147
	v_mov_b32_e32 v169, v64
	v_mov_b32_e32 v64, v133
	v_add_f32_e32 v132, v164, v165
	v_add_f32_e32 v133, v165, v164
	s_waitcnt lgkmcnt(1)
	v_add_f32_e32 v142, v165, v149
	s_waitcnt lgkmcnt(0)
	v_cndmask_b32_e64 v146, 0, v77, s[10:11]
	v_add_f32_e32 v142, v146, v142
	v_add_f32_e32 v146, v132, v149
	v_add_f32_e32 v147, v147, v132
	v_add_f32_e32 v146, v146, v77
	v_cndmask_b32_e64 v163, 0, v148, s[10:11]
	v_add_f32_e32 v147, v147, v149
	v_add_f32_e32 v146, v163, v146
	v_add_f32_e32 v147, v147, v77
	v_cndmask_b32_e64 v163, 0, v76, s[10:11]
	v_add_f32_e32 v76, v76, v148
	v_add_f32_e32 v77, v77, v149
	v_mov_b32_e32 v78, v80
	v_add_f32_e32 v147, v147, v148
	v_add_f32_e32 v77, v76, v77
	v_add_f32_e32 v76, v76, v76
	v_pk_mov_b32 v[80:81], v[80:81], v[132:133] op_sel:[1,0]
	v_add_f32_e32 v147, v163, v147
	v_add_f32_e32 v78, v78, v80
	v_add_f32_e32 v79, v79, v81
	v_mov_b32_e32 v163, v77
	v_add_f32_e32 v80, v162, v78
	v_add_f32_e32 v81, v163, v79
	v_add_f32_e32 v77, v80, v147
	v_add_f32_e32 v78, v168, v140
	v_add_f32_e32 v79, v169, v77
	v_add_f32_e32 v68, v68, v77
	v_add_f32_e32 v76, v78, v79
	v_mul_f32_e32 v76, 0x3fb8aa3b, v76
	v_exp_f32_e32 v76, v76
	v_add_f32_e32 v66, v66, v77
	v_add_f32_e32 v68, v70, v68
	v_add_f32_e32 v70, v130, v77
	v_cndmask_b32_e64 v78, 0, v76, s[14:15]
	v_add_f32_e32 v77, v80, v146
	v_add_f32_e32 v66, v140, v66
	v_add_f32_e32 v64, v64, v141
	v_add_f32_e32 v65, v65, v77
	v_mul_f32_e32 v66, 0x3fb8aa3b, v66
	v_add_f32_e32 v64, v64, v65
	v_add_f32_e32 v65, v67, v77
	v_exp_f32_e32 v66, v66
	v_add_f32_e32 v65, v141, v65
	v_mul_f32_e32 v64, 0x3fb8aa3b, v64
	v_mul_f32_e32 v65, 0x3fb8aa3b, v65
	v_exp_f32_e32 v64, v64
	v_exp_f32_e32 v65, v65
	v_cndmask_b32_e64 v79, 0, v66, s[18:19]
	v_add_f32_e32 v66, v69, v77
	v_add_f32_e32 v66, v71, v66
	v_mul_f32_e32 v66, 0x3fb8aa3b, v66
	v_cndmask_b32_e32 v71, 0, v64, vcc
	v_cndmask_b32_e64 v76, 0, v65, s[16:17]
	v_add_f32_e32 v171, v80, v142
	v_pk_mov_b32 v[64:65], v[72:73], v[134:135] op_sel:[1,0]
	v_exp_f32_e32 v66, v66
	v_add_f32_e32 v67, v131, v77
	v_add_f32_e32 v64, v64, v170
	v_add_f32_e32 v65, v65, v171
	v_add_f32_e32 v67, 0, v67
	v_add_f32_e32 v64, v64, v65
	v_add_f32_e32 v65, v135, v171
	v_mul_f32_e32 v67, 0x3fb8aa3b, v67
	v_mul_f32_e32 v64, 0x3fb8aa3b, v64
	v_add_f32_e32 v65, v170, v65
	v_exp_f32_e32 v67, v67
	v_exp_f32_e32 v64, v64
	v_mul_f32_e32 v65, 0x3fb8aa3b, v65
	v_add_f32_e32 v70, 0, v70
	v_cndmask_b32_e64 v77, 0, v66, s[22:23]
	v_exp_f32_e32 v140, v65
	v_add_f32_e32 v65, v136, v171
	v_add_f32_e32 v66, v137, v171
	v_mul_f32_e32 v68, 0x3fb8aa3b, v68
	v_mul_f32_e32 v70, 0x3fb8aa3b, v70
	v_add_f32_e32 v65, v139, v65
	v_add_f32_e32 v66, 0, v66
	v_exp_f32_e32 v68, v68
	v_exp_f32_e32 v70, v70
	v_mul_f32_e32 v65, 0x3fb8aa3b, v65
	v_mul_f32_e32 v66, 0x3fb8aa3b, v66
	v_cndmask_b32_e64 v131, 0, v67, s[26:27]
	v_exp_f32_e32 v139, v66
	v_exp_f32_e32 v141, v65
	v_cndmask_b32_e64 v146, 0, v64, s[36:37]
	ds_read_b64_tr_b16 v[64:65], v207 offset:34816
	ds_read_b64_tr_b16 v[66:67], v207 offset:37376
	v_cndmask_b32_e64 v138, 0, v149, s[10:11]
	v_add_f32_e32 v72, v80, v138
	v_mov_b32_e32 v142, v74
	v_cndmask_b32_e64 v130, 0, v68, s[24:25]
	v_cndmask_b32_e64 v70, 0, v70, s[34:35]
	v_add_f32_e32 v68, v72, v142
	v_add_f32_e32 v69, v166, v143
	v_cndmask_b32_e64 v74, 0, v139, s[28:29]
	v_add_f32_e32 v73, v68, v69
	v_cvt_pk_bf16_f32 v68, v78, v79
	v_cvt_pk_bf16_f32 v69, v130, v70
	v_cvt_pk_bf16_f32 v70, v71, v76
	v_cvt_pk_bf16_f32 v71, v77, v131
	ds_read_b64_tr_b16 v[76:77], v207 offset:34880
	ds_read_b64_tr_b16 v[130:131], v207 offset:34944
	ds_read_b64_tr_b16 v[134:135], v207 offset:35008
	ds_read_b64_tr_b16 v[78:79], v207 offset:37440
	ds_read_b64_tr_b16 v[132:133], v207 offset:37504
	ds_read_b64_tr_b16 v[136:137], v207 offset:37568
	s_waitcnt lgkmcnt(6)
	v_mfma_f32_32x32x16_bf16 v[48:63], v[64:67], v[68:71], v[48:63]
	v_mul_f32_e32 v64, 0x3fb8aa3b, v73
	v_exp_f32_e32 v64, v64
	v_add_f32_e32 v65, v72, v75
	v_add_f32_e32 v65, v65, v167
	v_mul_f32_e32 v65, 0x3fb8aa3b, v65
	v_cndmask_b32_e64 v139, 0, v64, s[42:43]
	v_add_f32_e32 v64, v72, v144
	v_exp_f32_e32 v75, v65
	v_add_f32_e32 v65, v72, v145
	v_add_f32_e32 v64, v64, v143
	v_add_f32_e32 v65, 0, v65
	v_mul_f32_e32 v64, 0x3fb8aa3b, v64
	v_mul_f32_e32 v65, 0x3fb8aa3b, v65
	v_exp_f32_e32 v64, v64
	v_exp_f32_e32 v72, v65
	s_waitcnt lgkmcnt(2)
	v_mfma_f32_32x32x16_bf16 v[32:47], v[76:79], v[68:71], v[32:47]
	v_cndmask_b32_e64 v73, 0, v140, s[20:21]
	v_cndmask_b32_e64 v138, 0, v141, s[30:31]
	v_cndmask_b32_e64 v76, 0, v64, s[44:45]
	v_cndmask_b32_e64 v72, 0, v72, s[40:41]
	ds_read_b64_tr_b16 v[64:65], v207 offset:39936
	ds_read_b64_tr_b16 v[66:67], v207 offset:42496
	v_add_f32_e32 v162, v80, v81
	s_mov_b32 s14, 0xc2480000
	s_waitcnt lgkmcnt(3)
	v_mfma_f32_32x32x16_bf16 v[16:31], v[130:133], v[68:71], v[16:31]
	v_cmp_gt_f32_e32 vcc, s14, v162
	s_cmp_eq_u64 vcc, exec
	s_cselect_b64 s[14:15], -1, 0
	s_waitcnt lgkmcnt(2)
	v_mfma_f32_32x32x16_bf16 v[0:15], v[134:137], v[68:71], v[0:15]
	v_cndmask_b32_e64 v71, 0, v75, s[38:39]
	v_cvt_pk_bf16_f32 v68, v146, v73
	v_cvt_pk_bf16_f32 v69, v138, v74
	v_cvt_pk_bf16_f32 v70, v139, v76
	v_cvt_pk_bf16_f32 v71, v71, v72
	ds_read_b64_tr_b16 v[72:73], v207 offset:40000
	ds_read_b64_tr_b16 v[76:77], v207 offset:40064
	ds_read_b64_tr_b16 v[130:131], v207 offset:40128
	ds_read_b64_tr_b16 v[74:75], v207 offset:42560
	ds_read_b64_tr_b16 v[78:79], v207 offset:42624
	ds_read_b64_tr_b16 v[132:133], v207 offset:42688
	s_waitcnt lgkmcnt(6)
	v_mfma_f32_32x32x16_bf16 v[48:63], v[64:67], v[68:71], v[48:63]
	s_waitcnt lgkmcnt(2)
	v_mfma_f32_32x32x16_bf16 v[32:47], v[72:75], v[68:71], v[32:47]
	s_waitcnt lgkmcnt(1)
	v_mfma_f32_32x32x16_bf16 v[16:31], v[76:79], v[68:71], v[16:31]
	s_waitcnt lgkmcnt(0)
	v_mfma_f32_32x32x16_bf16 v[0:15], v[130:133], v[68:71], v[0:15]
